# baseline (speedup 1.0000x reference)
; #define LAS __attribute__((address_space(3)))
; __device__ __forceinline__ float red8(float v) { v += dppf<0xB1>(v); v += dppf<0x4E>(v); v += dppf<0x141>(v); return v; }
; __device__ __forceinline__ void phase_scan(const ScanArgs& s, LAS unsigned char* lds, int wv) {
;     ...
;                 for (int t = 0; t < TC; ++t) {
;                     float w2[8], na2[8], bb2[8], kt2[8], r2[8]; f32x2 vv2;
;                     const int tn = (t + 1 < TC) ? t + 1 : t;
;                     ld8l(bp + tn * 64, w2); ld8l(bp + TC * 64 + tn * 64, na2); ld8l(bp + 2 * TC * 64 + tn * 64, bb2); ld8l(bp + 3 * TC * 64 + tn * 64, kt2); ld8l(bp + 4 * TC * 64 + tn * 64, r2);
;                     vv2 = *(const LAS f32x2*)((bp - ke) + 5 * TC * 64 + tn * 64 + rp);
;                     f32x2 p0 = SS[0] * na[0], p1 = SS[1] * na[1], p2 = SS[2] * na[2], p3 = SS[3] * na[3];
;                     p0 += SS[4] * na[4]; p1 += SS[5] * na[5]; p2 += SS[6] * na[6]; p3 += SS[7] * na[7];
;                     f32x2 tmp[8];
; #pragma unroll
;                     for (int j = 0; j < 8; ++j) tmp[j] = SS[j] * w[j] + vv * kt[j];
;                     f32x2 sa = (p0 + p1) + (p2 + p3);
;                     sa.x = red8(sa.x); sa.y = red8(sa.y);
; #pragma unroll
;                     for (int j = 0; j < 8; ++j) SS[j] = tmp[j] + sa * bb[j];
;                     f32x2 q0 = SS[0] * r[0], q1 = SS[1] * r[1], q2 = SS[2] * r[2], q3 = SS[3] * r[3];
;                     q0 += SS[4] * r[4]; q1 += SS[5] * r[5]; q2 += SS[6] * r[6]; q3 += SS[7] * r[7];
;                     f32x2 oo = (q0 + q1) + (q2 + q3);
;                     oo.x = red8(oo.x); oo.y = red8(oo.y);
;                     if ((lane & 7) == 0) *(LAS f32x2*)(ob + t * 64 + rp) = oo;
.LBB0_866:
	s_waitcnt lgkmcnt(0)
	v_pk_mul_f32 v[136:137], v[24:25], v[92:93] op_sel_hi:[0,1]
	s_waitcnt lgkmcnt(0)
	v_pk_fma_f32 v[136:137], v[32:33], v[108:109], v[136:137] op_sel_hi:[0,1,1]
	v_pk_mul_f32 v[24:25], v[24:25], v[94:95] op_sel:[1,0]
	v_pk_fma_f32 v[24:25], v[32:33], v[108:109], v[24:25] op_sel:[1,0,0]
	v_pk_mul_f32 v[32:33], v[26:27], v[96:97] op_sel_hi:[0,1]
	v_pk_fma_f32 v[32:33], v[34:35], v[108:109], v[32:33] op_sel_hi:[0,1,1]
	v_pk_mul_f32 v[26:27], v[26:27], v[98:99] op_sel:[1,0]
	v_pk_fma_f32 v[26:27], v[34:35], v[108:109], v[26:27] op_sel:[1,0,0]
	v_pk_mul_f32 v[34:35], v[16:17], v[106:107] op_sel_hi:[0,1]
	v_pk_fma_f32 v[34:35], v[28:29], v[108:109], v[34:35] op_sel_hi:[0,1,1]
	v_pk_mul_f32 v[16:17], v[16:17], v[104:105] op_sel:[1,0]
	v_pk_mul_f32 v[132:133], v[106:107], v[36:37] op_sel_hi:[1,0]
	v_pk_mul_f32 v[134:135], v[102:103], v[38:39] op_sel_hi:[1,0]
	v_pk_fma_f32 v[16:17], v[28:29], v[108:109], v[16:17] op_sel:[1,0,0]
	v_pk_mul_f32 v[28:29], v[18:19], v[102:103] op_sel_hi:[0,1]
	v_mov_b32_e32 v128, v21
	v_mov_b32_e32 v130, v23
	v_pk_mul_f32 v[36:37], v[104:105], v[36:37] op_sel:[0,1]
	v_pk_mul_f32 v[38:39], v[100:101], v[38:39] op_sel:[0,1]
	v_pk_fma_f32 v[28:29], v[30:31], v[108:109], v[28:29] op_sel_hi:[0,1,1]
	v_pk_mul_f32 v[18:19], v[18:19], v[100:101] op_sel:[1,0]
	v_pk_fma_f32 v[18:19], v[30:31], v[108:109], v[18:19] op_sel:[1,0,0]
	v_pk_fma_f32 v[20:21], v[92:93], v[20:21], v[132:133] op_sel_hi:[1,0,1]
	v_pk_fma_f32 v[30:31], v[94:95], v[128:129], v[36:37] op_sel_hi:[1,0,1]
	v_pk_fma_f32 v[22:23], v[96:97], v[22:23], v[134:135] op_sel_hi:[1,0,1]
	v_pk_fma_f32 v[36:37], v[98:99], v[130:131], v[38:39] op_sel_hi:[1,0,1]
	v_pk_add_f32 v[20:21], v[20:21], v[30:31]
	v_pk_add_f32 v[22:23], v[22:23], v[36:37]
	v_add_u32_e32 v44, s29, v123
	v_pk_add_f32 v[20:21], v[20:21], v[22:23]
	ds_read_b128 v[68:71], v44
	ds_read_b128 v[60:63], v44 offset:16
	ds_read_b128 v[56:59], v44 offset:8192
	ds_read_b128 v[76:79], v44 offset:8208
	ds_read_b128 v[52:55], v44 offset:16384
	ds_read_b128 v[48:51], v44 offset:16400
	ds_read_b128 v[72:75], v44 offset:24576
	ds_read_b128 v[64:67], v44 offset:24592
	ds_read_b128 v[40:43], v44 offset:32768
	ds_read_b128 v[44:47], v44 offset:32784
	v_mov_b32_dpp v22, v20 quad_perm:[1,0,3,2] row_mask:0xf bank_mask:0xf bound_ctrl:1
	v_mov_b32_dpp v23, v21 quad_perm:[1,0,3,2] row_mask:0xf bank_mask:0xf bound_ctrl:1
	v_pk_add_f32 v[20:21], v[20:21], v[22:23]
	v_add_u32_e32 v110, s29, v122
	ds_read_b64 v[110:111], v110
	v_mov_b32_dpp v22, v20 quad_perm:[2,3,0,1] row_mask:0xf bank_mask:0xf bound_ctrl:1
	v_mov_b32_dpp v23, v21 quad_perm:[2,3,0,1] row_mask:0xf bank_mask:0xf bound_ctrl:1
	v_pk_add_f32 v[20:21], v[20:21], v[22:23]
	v_add_u32_e32 v127, s29, v124
	s_nop 0
	v_mov_b32_dpp v22, v20 row_half_mirror row_mask:0xf bank_mask:0xf bound_ctrl:1
	v_mov_b32_dpp v23, v21 row_half_mirror row_mask:0xf bank_mask:0xf bound_ctrl:1
	v_pk_add_f32 v[20:21], v[20:21], v[22:23]
	s_nop 0
	v_pk_fma_f32 v[92:93], v[4:5], v[20:21], v[136:137] op_sel_hi:[0,1,1]
	v_pk_fma_f32 v[94:95], v[4:5], v[20:21], v[24:25] op_sel:[1,0,0]
	v_mov_b32_e32 v4, v7
	v_pk_fma_f32 v[106:107], v[0:1], v[20:21], v[34:35] op_sel_hi:[0,1,1]
	v_pk_fma_f32 v[96:97], v[6:7], v[20:21], v[32:33] op_sel_hi:[0,1,1]
	v_pk_fma_f32 v[98:99], v[4:5], v[20:21], v[26:27] op_sel_hi:[0,1,1]
	v_pk_fma_f32 v[104:105], v[0:1], v[20:21], v[16:17] op_sel:[1,0,0]
	v_mov_b32_e32 v0, v3
	v_pk_mul_f32 v[4:5], v[12:13], v[106:107] op_sel_hi:[0,1]
	v_mov_b32_e32 v6, v13
	v_pk_fma_f32 v[102:103], v[2:3], v[20:21], v[28:29] op_sel_hi:[0,1,1]
	v_pk_fma_f32 v[100:101], v[0:1], v[20:21], v[18:19] op_sel_hi:[0,1,1]
	v_mov_b32_e32 v0, v9
	v_pk_fma_f32 v[4:5], v[8:9], v[92:93], v[4:5] op_sel_hi:[0,1,1]
	v_pk_mul_f32 v[6:7], v[6:7], v[104:105] op_sel_hi:[0,1]
	v_mov_b32_e32 v8, v15
	v_mov_b32_e32 v2, v11
	v_pk_fma_f32 v[0:1], v[0:1], v[94:95], v[6:7] op_sel_hi:[0,1,1]
	v_pk_mul_f32 v[6:7], v[14:15], v[102:103] op_sel_hi:[0,1]
	v_pk_mul_f32 v[8:9], v[8:9], v[100:101] op_sel_hi:[0,1]
	v_pk_fma_f32 v[6:7], v[10:11], v[96:97], v[6:7] op_sel_hi:[0,1,1]
	v_pk_fma_f32 v[2:3], v[2:3], v[98:99], v[8:9] op_sel_hi:[0,1,1]
	v_pk_add_f32 v[0:1], v[4:5], v[0:1]
	v_pk_add_f32 v[2:3], v[6:7], v[2:3]
	s_nop 0
	v_pk_add_f32 v[0:1], v[0:1], v[2:3]
	s_nop 1
	v_mov_b32_dpp v2, v0 quad_perm:[1,0,3,2] row_mask:0xf bank_mask:0xf bound_ctrl:1
	v_mov_b32_dpp v3, v1 quad_perm:[1,0,3,2] row_mask:0xf bank_mask:0xf bound_ctrl:1
	v_pk_add_f32 v[0:1], v[0:1], v[2:3]
	s_nop 1
	v_mov_b32_dpp v2, v0 quad_perm:[2,3,0,1] row_mask:0xf bank_mask:0xf bound_ctrl:1
	v_mov_b32_dpp v3, v1 quad_perm:[2,3,0,1] row_mask:0xf bank_mask:0xf bound_ctrl:1
	v_pk_add_f32 v[0:1], v[0:1], v[2:3]
	s_nop 1
	v_mov_b32_dpp v2, v0 row_half_mirror row_mask:0xf bank_mask:0xf bound_ctrl:1
	v_mov_b32_dpp v3, v1 row_half_mirror row_mask:0xf bank_mask:0xf bound_ctrl:1
	s_and_saveexec_b64 s[8:9], s[44:45]
	v_add_u32_e32 v4, 0x18000, v127
	v_pk_add_f32 v[0:1], v[0:1], v[2:3]
	ds_write_b64 v4, v[0:1]
	s_or_b64 exec, exec, s[8:9]
	s_waitcnt lgkmcnt(0)
; #define LAS __attribute__((address_space(3)))
; __device__ __forceinline__ float red8(float v) { v += dppf<0xB1>(v); v += dppf<0x4E>(v); v += dppf<0x141>(v); return v; }
; __device__ __forceinline__ void phase_scan(const ScanArgs& s, LAS unsigned char* lds, int wv) {
;     ...
;                 for (int t = 0; t < TC; ++t) {
;                     float w2[8], na2[8], bb2[8], kt2[8], r2[8]; f32x2 vv2;
;                     const int tn = (t + 1 < TC) ? t + 1 : t;
;                     ld8l(bp + tn * 64, w2); ld8l(bp + TC * 64 + tn * 64, na2); ld8l(bp + 2 * TC * 64 + tn * 64, bb2); ld8l(bp + 3 * TC * 64 + tn * 64, kt2); ld8l(bp + 4 * TC * 64 + tn * 64, r2);
;                     vv2 = *(const LAS f32x2*)((bp - ke) + 5 * TC * 64 + tn * 64 + rp);
;                     f32x2 p0 = SS[0] * na[0], p1 = SS[1] * na[1], p2 = SS[2] * na[2], p3 = SS[3] * na[3];
;                     p0 += SS[4] * na[4]; p1 += SS[5] * na[5]; p2 += SS[6] * na[6]; p3 += SS[7] * na[7];
;                     f32x2 tmp[8];
; #pragma unroll
;                     for (int j = 0; j < 8; ++j) tmp[j] = SS[j] * w[j] + vv * kt[j];
;                     f32x2 sa = (p0 + p1) + (p2 + p3);
;                     sa.x = red8(sa.x); sa.y = red8(sa.y);
; #pragma unroll
;                     for (int j = 0; j < 8; ++j) SS[j] = tmp[j] + sa * bb[j];
;                     f32x2 q0 = SS[0] * r[0], q1 = SS[1] * r[1], q2 = SS[2] * r[2], q3 = SS[3] * r[3];
;                     q0 += SS[4] * r[4]; q1 += SS[5] * r[5]; q2 += SS[6] * r[6]; q3 += SS[7] * r[7];
;                     f32x2 oo = (q0 + q1) + (q2 + q3);
;                     oo.x = red8(oo.x); oo.y = red8(oo.y);
;                     if ((lane & 7) == 0) *(LAS f32x2*)(ob + t * 64 + rp) = oo;
; #pragma unroll
;                     for (int j = 0; j < 8; ++j) { w[j] = w2[j]; na[j] = na2[j]; bb[j] = bb2[j]; kt[j] = kt2[j]; r[j] = r2[j]; }
;                     vv = vv2;
;                 }
	v_pk_mul_f32 v[134:135], v[68:69], v[92:93] op_sel_hi:[0,1]
	v_pk_mul_f32 v[68:69], v[68:69], v[94:95] op_sel:[1,0]
	s_waitcnt lgkmcnt(0)
	v_pk_fma_f32 v[134:135], v[72:73], v[110:111], v[134:135] op_sel_hi:[0,1,1]
	v_pk_fma_f32 v[68:69], v[72:73], v[110:111], v[68:69] op_sel:[1,0,0]
	v_pk_mul_f32 v[72:73], v[70:71], v[96:97] op_sel_hi:[0,1]
	v_pk_fma_f32 v[72:73], v[74:75], v[110:111], v[72:73] op_sel_hi:[0,1,1]
	v_pk_mul_f32 v[70:71], v[70:71], v[98:99] op_sel:[1,0]
	v_pk_fma_f32 v[70:71], v[74:75], v[110:111], v[70:71] op_sel:[1,0,0]
	v_pk_mul_f32 v[74:75], v[60:61], v[106:107] op_sel_hi:[0,1]
	v_pk_mul_f32 v[60:61], v[60:61], v[104:105] op_sel:[1,0]
	v_pk_mul_f32 v[132:133], v[102:103], v[78:79] op_sel_hi:[1,0]
	v_pk_fma_f32 v[74:75], v[64:65], v[110:111], v[74:75] op_sel_hi:[0,1,1]
	v_pk_fma_f32 v[60:61], v[64:65], v[110:111], v[60:61] op_sel:[1,0,0]
	v_pk_mul_f32 v[64:65], v[62:63], v[102:103] op_sel_hi:[0,1]
	v_mov_b32_e32 v128, v59
	v_pk_mul_f32 v[130:131], v[106:107], v[76:77] op_sel_hi:[1,0]
	v_pk_mul_f32 v[76:77], v[104:105], v[76:77] op_sel:[0,1]
	v_pk_mul_f32 v[78:79], v[100:101], v[78:79] op_sel:[0,1]
	v_pk_fma_f32 v[64:65], v[66:67], v[110:111], v[64:65] op_sel_hi:[0,1,1]
	v_pk_mul_f32 v[62:63], v[62:63], v[100:101] op_sel:[1,0]
	v_pk_fma_f32 v[62:63], v[66:67], v[110:111], v[62:63] op_sel:[1,0,0]
	v_pk_fma_f32 v[66:67], v[92:93], v[56:57], v[130:131] op_sel_hi:[1,0,1]
	v_pk_fma_f32 v[56:57], v[94:95], v[56:57], v[76:77] op_sel:[0,1,0]
	v_pk_fma_f32 v[58:59], v[96:97], v[58:59], v[132:133] op_sel_hi:[1,0,1]
	v_pk_fma_f32 v[76:77], v[98:99], v[128:129], v[78:79] op_sel_hi:[1,0,1]
	v_pk_add_f32 v[56:57], v[66:67], v[56:57]
	v_pk_add_f32 v[58:59], v[58:59], v[76:77]
	s_cmpk_lg_i32 s29, 0x1e00
	v_pk_add_f32 v[56:57], v[56:57], v[58:59]
	s_cselect_b32 s8, s30, 0x7c0
	s_lshl_b32 s8, s8, 2
	v_mov_b32_dpp v58, v56 quad_perm:[1,0,3,2] row_mask:0xf bank_mask:0xf bound_ctrl:1
	v_mov_b32_dpp v59, v57 quad_perm:[1,0,3,2] row_mask:0xf bank_mask:0xf bound_ctrl:1
	v_pk_add_f32 v[56:57], v[56:57], v[58:59]
	v_add_u32_e32 v12, s8, v125
	ds_read_b128 v[24:27], v12
	ds_read_b128 v[16:19], v12 offset:16
	ds_read_b128 v[20:23], v12 offset:8192
	ds_read_b128 v[36:39], v12 offset:8208
	ds_read_b128 v[4:7], v12 offset:16384
	ds_read_b128 v[0:3], v12 offset:16400
	ds_read_b128 v[32:35], v12 offset:24576
	ds_read_b128 v[28:31], v12 offset:24592
	ds_read_b128 v[8:11], v12 offset:32768
	ds_read_b128 v[12:15], v12 offset:32784
	v_mov_b32_dpp v58, v56 quad_perm:[2,3,0,1] row_mask:0xf bank_mask:0xf bound_ctrl:1
	v_mov_b32_dpp v59, v57 quad_perm:[2,3,0,1] row_mask:0xf bank_mask:0xf bound_ctrl:1
	v_pk_add_f32 v[56:57], v[56:57], v[58:59]
	v_add_u32_e32 v108, s8, v126
	ds_read_b64 v[108:109], v108 offset:40960
	v_mov_b32_dpp v58, v56 row_half_mirror row_mask:0xf bank_mask:0xf bound_ctrl:1
	v_mov_b32_dpp v59, v57 row_half_mirror row_mask:0xf bank_mask:0xf bound_ctrl:1
	v_pk_add_f32 v[56:57], v[56:57], v[58:59]
	s_nop 0
	v_pk_fma_f32 v[106:107], v[48:49], v[56:57], v[74:75] op_sel_hi:[0,1,1]
	v_pk_fma_f32 v[104:105], v[48:49], v[56:57], v[60:61] op_sel:[1,0,0]
	v_pk_fma_f32 v[92:93], v[52:53], v[56:57], v[134:135] op_sel_hi:[0,1,1]
	v_pk_fma_f32 v[94:95], v[52:53], v[56:57], v[68:69] op_sel:[1,0,0]
	v_pk_fma_f32 v[102:103], v[50:51], v[56:57], v[64:65] op_sel_hi:[0,1,1]
	v_mov_b32_e32 v48, v51
	v_pk_mul_f32 v[50:51], v[44:45], v[106:107] op_sel_hi:[0,1]
	v_pk_mul_f32 v[44:45], v[44:45], v[104:105] op_sel:[1,0]
	v_pk_fma_f32 v[96:97], v[54:55], v[56:57], v[72:73] op_sel_hi:[0,1,1]
	v_pk_fma_f32 v[50:51], v[40:41], v[92:93], v[50:51] op_sel_hi:[0,1,1]
	v_pk_fma_f32 v[40:41], v[40:41], v[94:95], v[44:45] op_sel:[1,0,0]
	v_pk_mul_f32 v[44:45], v[46:47], v[102:103] op_sel_hi:[0,1]
	v_mov_b32_e32 v52, v55
	v_pk_fma_f32 v[100:101], v[48:49], v[56:57], v[62:63] op_sel_hi:[0,1,1]
	v_mov_b32_e32 v48, v43
	v_pk_fma_f32 v[42:43], v[42:43], v[96:97], v[44:45] op_sel_hi:[0,1,1]
	v_mov_b32_e32 v44, v47
	v_pk_fma_f32 v[98:99], v[52:53], v[56:57], v[70:71] op_sel_hi:[0,1,1]
	v_pk_mul_f32 v[44:45], v[44:45], v[100:101] op_sel_hi:[0,1]
	v_pk_fma_f32 v[44:45], v[48:49], v[98:99], v[44:45] op_sel_hi:[0,1,1]
	v_pk_add_f32 v[40:41], v[50:51], v[40:41]
	v_pk_add_f32 v[42:43], v[42:43], v[44:45]
	s_nop 0
	v_pk_add_f32 v[40:41], v[40:41], v[42:43]
	s_nop 1
	v_mov_b32_dpp v42, v40 quad_perm:[1,0,3,2] row_mask:0xf bank_mask:0xf bound_ctrl:1
	v_mov_b32_dpp v43, v41 quad_perm:[1,0,3,2] row_mask:0xf bank_mask:0xf bound_ctrl:1
	v_pk_add_f32 v[40:41], v[40:41], v[42:43]
	s_nop 1
	v_mov_b32_dpp v42, v40 quad_perm:[2,3,0,1] row_mask:0xf bank_mask:0xf bound_ctrl:1
	v_mov_b32_dpp v43, v41 quad_perm:[2,3,0,1] row_mask:0xf bank_mask:0xf bound_ctrl:1
	v_pk_add_f32 v[40:41], v[40:41], v[42:43]
	s_nop 1
	v_mov_b32_dpp v42, v40 row_half_mirror row_mask:0xf bank_mask:0xf bound_ctrl:1
	v_mov_b32_dpp v43, v41 row_half_mirror row_mask:0xf bank_mask:0xf bound_ctrl:1
	s_and_saveexec_b64 s[8:9], s[44:45]
	s_cbranch_execz .LBB0_865
	v_add_u32_e32 v44, 0x18100, v127
	v_pk_add_f32 v[40:41], v[40:41], v[42:43]
	ds_write_b64 v44, v[40:41]
	s_branch .LBB0_865
